# scan tail: quad sum-of-squares reduction via two DPP adds instead of two ds_bpermute round trips
# speedup vs baseline: 1.0006x; 1.0006x over previous
.LBB0_422:
	s_or_b64 exec, exec, s[36:37]
	s_waitcnt lgkmcnt(0)
	s_barrier
	v_mov_b32_e32 v232, v156
	v_ashrrev_i32_e32 v233, 31, v156
	v_lshl_add_u64 v[232:233], v[232:233], 0, s[46:47]
	v_lshlrev_b64 v[232:233], 8, v[232:233]
	v_lshl_add_u64 v[232:233], v[150:151], 0, v[232:233]
	global_load_dwordx4 v[216:219], v[232:233], off offset:192
	global_load_dwordx4 v[220:223], v[232:233], off offset:128
	global_load_dwordx4 v[224:227], v[232:233], off offset:64
	global_load_dwordx4 v[228:231], v[232:233], off
	ds_read_b128 v[0:3], v167
	ds_read_b128 v[4:7], v167 offset:416
	ds_read_b128 v[8:11], v167 offset:448
	v_add_u32_e32 v157, v170, v179
	s_add_u32 s52, s52, 0x4000
	s_waitcnt lgkmcnt(2)
	v_pk_mul_f32 v[48:49], v[108:109], v[0:1]
	v_pk_mul_f32 v[50:51], v[114:115], v[2:3]
	ds_read_b128 v[0:3], v167 offset:32
	ds_read_b128 v[12:15], v167 offset:480
	v_cvt_pk_bf16_f32 v64, v48, v49
	v_cvt_pk_bf16_f32 v65, v50, v51
	s_waitcnt lgkmcnt(3)
	v_pk_mul_f32 v[4:5], v[144:145], v[4:5]
	s_waitcnt lgkmcnt(1)
	v_pk_mul_f32 v[52:53], v[52:53], v[0:1]
	v_pk_mul_f32 v[54:55], v[54:55], v[2:3]
	ds_read_b128 v[0:3], v167 offset:64
	v_cvt_pk_bf16_f32 v66, v52, v53
	v_cvt_pk_bf16_f32 v67, v54, v55
	v_pk_mul_f32 v[6:7], v[138:139], v[6:7]
	v_pk_mul_f32 v[8:9], v[146:147], v[8:9]
	s_waitcnt lgkmcnt(0)
	v_pk_mul_f32 v[56:57], v[56:57], v[0:1]
	v_pk_mul_f32 v[58:59], v[58:59], v[2:3]
	ds_read_b128 v[0:3], v167 offset:96
	v_pk_mul_f32 v[10:11], v[140:141], v[10:11]
	v_pk_mul_f32 v[12:13], v[148:149], v[12:13]
	v_pk_mul_f32 v[14:15], v[142:143], v[14:15]
	s_addc_u32 s53, s53, 0
	s_waitcnt lgkmcnt(0)
	v_pk_mul_f32 v[60:61], v[60:61], v[0:1]
	v_pk_mul_f32 v[62:63], v[62:63], v[2:3]
	ds_read_b128 v[0:3], v167 offset:128
	s_cmp_eq_u32 s52, 0x20000
	s_waitcnt lgkmcnt(0)
	v_pk_mul_f32 v[32:33], v[100:101], v[0:1]
	v_pk_mul_f32 v[34:35], v[96:97], v[2:3]
	ds_read_b128 v[0:3], v167 offset:160
	v_cvt_pk_bf16_f32 v100, v56, v57
	v_cvt_pk_bf16_f32 v101, v58, v59
	s_waitcnt lgkmcnt(0)
	v_pk_mul_f32 v[36:37], v[110:111], v[0:1]
	v_pk_mul_f32 v[38:39], v[102:103], v[2:3]
	ds_read_b128 v[0:3], v167 offset:192
	v_cvt_pk_bf16_f32 v102, v60, v61
	v_cvt_pk_bf16_f32 v103, v62, v63
	s_waitcnt lgkmcnt(0)
	v_pk_mul_f32 v[40:41], v[104:105], v[0:1]
	v_pk_mul_f32 v[42:43], v[98:99], v[2:3]
	ds_read_b128 v[0:3], v167 offset:224
	v_add_u32_e32 v104, 0x2000, v180
	s_waitcnt lgkmcnt(0)
	v_pk_mul_f32 v[44:45], v[116:117], v[0:1]
	v_pk_mul_f32 v[46:47], v[106:107], v[2:3]
	ds_read_b128 v[0:3], v167 offset:256
	s_waitcnt lgkmcnt(0)
	v_pk_mul_f32 v[16:17], v[122:123], v[0:1]
	v_pk_mul_f32 v[18:19], v[118:119], v[2:3]
	ds_read_b128 v[0:3], v167 offset:288
	s_waitcnt lgkmcnt(0)
	v_pk_mul_f32 v[20:21], v[130:131], v[0:1]
	v_pk_mul_f32 v[22:23], v[124:125], v[2:3]
	ds_read_b128 v[0:3], v167 offset:320
	s_waitcnt lgkmcnt(0)
	v_pk_mul_f32 v[24:25], v[126:127], v[0:1]
	v_pk_mul_f32 v[26:27], v[120:121], v[2:3]
	ds_read_b128 v[0:3], v167 offset:352
	s_waitcnt lgkmcnt(0)
	v_pk_mul_f32 v[28:29], v[132:133], v[0:1]
	v_pk_mul_f32 v[30:31], v[128:129], v[2:3]
	ds_read_b128 v[0:3], v167 offset:384
	ds_read2_b64 v[68:71], v180 offset1:2
	ds_read2_b64 v[96:99], v180 offset0:4 offset1:6
	s_waitcnt lgkmcnt(1)
	v_mfma_f32_32x32x16_bf16 v[80:95], v[64:67], v[68:71], 0
	ds_read2_b64 v[68:71], v104 offset0:64 offset1:66
	v_mul_f32_e64 v0, v136, v0
	v_mul_f32_e64 v1, v137, v1
	v_mul_f32_e64 v2, v134, v2
	v_mul_f32_e64 v3, v135, v3
	s_waitcnt lgkmcnt(0)
	v_mfma_f32_32x32x16_bf16 v[64:79], v[64:67], v[68:71], 0
	v_mfma_f32_32x32x16_bf16 v[80:95], v[100:103], v[96:99], v[80:95]
	ds_read2_b64 v[96:99], v104 offset0:68 offset1:70
	s_waitcnt lgkmcnt(0)
	v_mfma_f32_32x32x16_bf16 v[64:79], v[100:103], v[96:99], v[64:79]
	v_cvt_pk_bf16_f32 v96, v32, v33
	v_cvt_pk_bf16_f32 v97, v34, v35
	v_cvt_pk_bf16_f32 v98, v36, v37
	v_cvt_pk_bf16_f32 v99, v38, v39
	ds_read2_b64 v[100:103], v180 offset0:8 offset1:10
	s_waitcnt lgkmcnt(0)
	v_mfma_f32_32x32x16_bf16 v[80:95], v[96:99], v[100:103], v[80:95]
	ds_read2_b64 v[100:103], v104 offset0:72 offset1:74
	s_waitcnt lgkmcnt(0)
	v_mfma_f32_32x32x16_bf16 v[64:79], v[96:99], v[100:103], v[64:79]
	v_cvt_pk_bf16_f32 v96, v40, v41
	v_cvt_pk_bf16_f32 v97, v42, v43
	v_cvt_pk_bf16_f32 v98, v44, v45
	v_cvt_pk_bf16_f32 v99, v46, v47
	ds_read2_b64 v[100:103], v180 offset0:12 offset1:14
	s_waitcnt lgkmcnt(0)
	v_mfma_f32_32x32x16_bf16 v[80:95], v[96:99], v[100:103], v[80:95]
	ds_read2_b64 v[100:103], v104 offset0:76 offset1:78
	s_waitcnt lgkmcnt(0)
	v_mfma_f32_32x32x16_bf16 v[64:79], v[96:99], v[100:103], v[64:79]
	v_cvt_pk_bf16_f32 v96, v16, v17
	v_cvt_pk_bf16_f32 v97, v18, v19
	v_cvt_pk_bf16_f32 v98, v20, v21
	v_cvt_pk_bf16_f32 v99, v22, v23
	ds_read2_b64 v[100:103], v180 offset0:16 offset1:18
	s_waitcnt lgkmcnt(0)
	v_mfma_f32_32x32x16_bf16 v[80:95], v[96:99], v[100:103], v[80:95]
	ds_read2_b64 v[100:103], v104 offset0:80 offset1:82
	s_waitcnt lgkmcnt(0)
	v_mfma_f32_32x32x16_bf16 v[64:79], v[96:99], v[100:103], v[64:79]
	v_cvt_pk_bf16_f32 v96, v24, v25
	v_cvt_pk_bf16_f32 v97, v26, v27
	v_cvt_pk_bf16_f32 v98, v28, v29
	v_cvt_pk_bf16_f32 v99, v30, v31
	ds_read2_b64 v[100:103], v180 offset0:20 offset1:22
	s_waitcnt lgkmcnt(0)
	v_mfma_f32_32x32x16_bf16 v[80:95], v[96:99], v[100:103], v[80:95]
	ds_read2_b64 v[100:103], v104 offset0:84 offset1:86
	s_waitcnt lgkmcnt(0)
	v_mfma_f32_32x32x16_bf16 v[64:79], v[96:99], v[100:103], v[64:79]
	v_cvt_pk_bf16_f32 v96, v0, v1
	v_cvt_pk_bf16_f32 v97, v2, v3
	v_cvt_pk_bf16_f32 v98, v4, v5
	v_cvt_pk_bf16_f32 v99, v6, v7
	ds_read2_b64 v[100:103], v180 offset0:24 offset1:26
	s_waitcnt lgkmcnt(0)
	v_mfma_f32_32x32x16_bf16 v[80:95], v[96:99], v[100:103], v[80:95]
	ds_read2_b64 v[100:103], v104 offset0:88 offset1:90
	s_waitcnt lgkmcnt(0)
	v_mfma_f32_32x32x16_bf16 v[64:79], v[96:99], v[100:103], v[64:79]
	v_cvt_pk_bf16_f32 v96, v8, v9
	v_cvt_pk_bf16_f32 v97, v10, v11
	v_cvt_pk_bf16_f32 v98, v12, v13
	v_cvt_pk_bf16_f32 v99, v14, v15
	ds_read2_b64 v[100:103], v180 offset0:28 offset1:30
	s_waitcnt lgkmcnt(0)
	v_mfma_f32_32x32x16_bf16 v[80:95], v[96:99], v[100:103], v[80:95]
	ds_read2_b64 v[100:103], v104 offset0:92 offset1:94
	s_waitcnt lgkmcnt(0)
	v_mfma_f32_32x32x16_bf16 v[64:79], v[96:99], v[100:103], v[64:79]
	ds_read_b128 v[114:117], v157 offset:17408
	ds_read_b128 v[96:99], v157
	ds_read_b128 v[118:121], v157 offset:32
	ds_read_b128 v[122:125], v157 offset:17440
	s_waitcnt lgkmcnt(2)
	v_mfma_f32_32x32x16_bf16 v[96:111], v[114:117], v[96:99], 0
	s_waitcnt lgkmcnt(0)
	v_mfma_f32_32x32x16_bf16 v[96:111], v[122:125], v[118:121], v[96:111]
	ds_read_b128 v[118:121], v157 offset:17472
	ds_read_b128 v[126:129], v157 offset:64
	s_waitcnt lgkmcnt(0)
	v_mfma_f32_32x32x16_bf16 v[96:111], v[118:121], v[126:129], v[96:111]
	ds_read_b128 v[126:129], v157 offset:17504
	ds_read_b128 v[130:133], v157 offset:96
	s_waitcnt lgkmcnt(0)
	v_mfma_f32_32x32x16_bf16 v[96:111], v[126:129], v[130:133], v[96:111]
	ds_read_b128 v[130:133], v157 offset:17536
	ds_read_b128 v[134:137], v157 offset:128
	s_waitcnt lgkmcnt(0)
	v_mfma_f32_32x32x16_bf16 v[96:111], v[130:133], v[134:137], v[96:111]
	ds_read_b128 v[134:137], v157 offset:17568
	ds_read_b128 v[138:141], v157 offset:160
	s_waitcnt lgkmcnt(0)
	v_mfma_f32_32x32x16_bf16 v[96:111], v[134:137], v[138:141], v[96:111]
	ds_read_b128 v[138:141], v157 offset:17600
	ds_read_b128 v[142:145], v157 offset:192
	s_waitcnt lgkmcnt(0)
	v_mfma_f32_32x32x16_bf16 v[96:111], v[138:141], v[142:145], v[96:111]
	ds_read_b128 v[142:145], v157 offset:17632
	ds_read_b128 v[146:149], v157 offset:224
	s_waitcnt lgkmcnt(0)
	v_mfma_f32_32x32x16_bf16 v[96:111], v[142:145], v[146:149], v[96:111]
	s_nop 11
	v_cndmask_b32_e64 v146, v96, 0, s[34:35]
	v_cndmask_b32_e64 v96, v146, v96, s[30:31]
	v_cndmask_b32_e64 v97, 0, v97, s[30:31]
	v_cndmask_b32_e64 v98, v98, 0, s[28:29]
	v_cndmask_b32_e64 v99, v99, 0, s[26:27]
	v_cndmask_b32_e64 v100, v100, 0, s[24:25]
	v_cndmask_b32_e64 v101, v101, 0, s[22:23]
	v_cvt_pk_bf16_f32 v96, v96, v97
	v_cvt_pk_bf16_f32 v97, v98, v99
	v_cvt_pk_bf16_f32 v98, v100, v101
	v_add_u32_e32 v100, v171, v168
	v_add_u32_e32 v183, 0xd000, v100
	ds_read2_b64 v[146:149], v183 offset1:2
	ds_read2_b64 v[184:187], v183 offset0:4 offset1:6
	v_cndmask_b32_e64 v102, v102, 0, s[20:21]
	v_cndmask_b32_e64 v103, v103, 0, s[18:19]
	v_cvt_pk_bf16_f32 v99, v102, v103
	ds_read_b128 v[188:191], v157 offset:8704
	v_cndmask_b32_e64 v104, v104, 0, s[16:17]
	s_waitcnt lgkmcnt(2)
	v_mfma_f32_32x32x16_bf16 v[80:95], v[146:149], v[96:99], v[80:95]
	v_cndmask_b32_e64 v105, v105, 0, s[14:15]
	v_cndmask_b32_e64 v106, v106, 0, s[12:13]
	v_cndmask_b32_e64 v107, v107, 0, s[10:11]
	v_cndmask_b32_e64 v108, v108, 0, s[8:9]
	v_cndmask_b32_e64 v109, v109, 0, s[6:7]
	v_cndmask_b32_e64 v110, v110, 0, s[4:5]
	v_cndmask_b32_e64 v111, v111, 0, s[2:3]
	v_cvt_pk_bf16_f32 v96, v104, v105
	v_cvt_pk_bf16_f32 v97, v106, v107
	v_cvt_pk_bf16_f32 v98, v108, v109
	v_cvt_pk_bf16_f32 v99, v110, v111
	s_waitcnt lgkmcnt(1)
	s_nop 0
	v_mfma_f32_32x32x16_bf16 v[80:95], v[184:187], v[96:99], v[80:95]
	s_waitcnt lgkmcnt(0)
	v_mfma_f32_32x32x16_bf16 v[96:111], v[114:117], v[188:191], 0
	ds_read_b128 v[114:117], v157 offset:8736
	s_waitcnt lgkmcnt(0)
	v_mfma_f32_32x32x16_bf16 v[96:111], v[122:125], v[114:117], v[96:111]
	ds_read_b128 v[122:125], v157 offset:8768
	s_waitcnt lgkmcnt(0)
	v_mfma_f32_32x32x16_bf16 v[96:111], v[118:121], v[122:125], v[96:111]
	ds_read_b128 v[118:121], v157 offset:8800
	s_waitcnt lgkmcnt(0)
	v_mfma_f32_32x32x16_bf16 v[96:111], v[126:129], v[118:121], v[96:111]
	ds_read_b128 v[126:129], v157 offset:8832
	s_waitcnt lgkmcnt(0)
	v_mfma_f32_32x32x16_bf16 v[96:111], v[130:133], v[126:129], v[96:111]
	ds_read_b128 v[130:133], v157 offset:8864
	s_waitcnt lgkmcnt(0)
	v_mfma_f32_32x32x16_bf16 v[96:111], v[134:137], v[130:133], v[96:111]
	ds_read_b128 v[134:137], v157 offset:8896
	s_waitcnt lgkmcnt(0)
	v_mfma_f32_32x32x16_bf16 v[96:111], v[138:141], v[134:137], v[96:111]
	ds_read_b128 v[138:141], v157 offset:8928
	s_waitcnt lgkmcnt(0)
	v_mfma_f32_32x32x16_bf16 v[96:111], v[142:145], v[138:141], v[96:111]
	ds_read_b128 v[142:145], v157 offset:26144
	s_nop 10
	v_cvt_pk_bf16_f32 v96, v96, v97
	v_cvt_pk_bf16_f32 v97, v98, v99
	v_cvt_pk_bf16_f32 v98, v100, v101
	v_cvt_pk_bf16_f32 v99, v102, v103
	s_nop 1
	v_mfma_f32_32x32x16_bf16 v[64:79], v[146:149], v[96:99], v[64:79]
	v_cvt_pk_bf16_f32 v96, v104, v105
	v_cvt_pk_bf16_f32 v97, v106, v107
	v_cvt_pk_bf16_f32 v98, v108, v109
	v_cvt_pk_bf16_f32 v99, v110, v111
	s_nop 1
	v_mfma_f32_32x32x16_bf16 v[64:79], v[184:187], v[96:99], v[64:79]
	ds_read_b128 v[96:99], v157 offset:26112
	s_waitcnt lgkmcnt(0)
	v_mfma_f32_32x32x16_bf16 v[96:111], v[96:99], v[188:191], 0
	v_mfma_f32_32x32x16_bf16 v[96:111], v[142:145], v[114:117], v[96:111]
	ds_read_b128 v[114:117], v157 offset:26176
	s_waitcnt lgkmcnt(0)
	v_mfma_f32_32x32x16_bf16 v[96:111], v[114:117], v[122:125], v[96:111]
	ds_read_b128 v[114:117], v157 offset:26208
	s_waitcnt lgkmcnt(0)
	v_mfma_f32_32x32x16_bf16 v[96:111], v[114:117], v[118:121], v[96:111]
	ds_read_b128 v[114:117], v157 offset:26240
	s_waitcnt lgkmcnt(0)
	v_mfma_f32_32x32x16_bf16 v[96:111], v[114:117], v[126:129], v[96:111]
	ds_read_b128 v[114:117], v157 offset:26272
	s_waitcnt lgkmcnt(0)
	v_mfma_f32_32x32x16_bf16 v[96:111], v[114:117], v[130:133], v[96:111]
	ds_read_b128 v[114:117], v157 offset:26304
	s_waitcnt lgkmcnt(0)
	v_mfma_f32_32x32x16_bf16 v[96:111], v[114:117], v[134:137], v[96:111]
	ds_read_b128 v[114:117], v157 offset:26336
	v_ashrrev_i32_e32 v157, 31, v156
	s_waitcnt lgkmcnt(0)
	v_mfma_f32_32x32x16_bf16 v[96:111], v[114:117], v[138:141], v[96:111]
	s_nop 11
	v_cndmask_b32_e64 v114, v96, 0, s[34:35]
	v_cndmask_b32_e64 v96, v114, v96, s[30:31]
	v_cndmask_b32_e64 v97, 0, v97, s[30:31]
	v_cndmask_b32_e64 v98, v98, 0, s[28:29]
	v_cndmask_b32_e64 v99, v99, 0, s[26:27]
	v_cndmask_b32_e64 v100, v100, 0, s[24:25]
	v_cndmask_b32_e64 v101, v101, 0, s[22:23]
	v_cndmask_b32_e64 v102, v102, 0, s[20:21]
	v_cndmask_b32_e64 v103, v103, 0, s[18:19]
	v_cvt_pk_bf16_f32 v96, v96, v97
	v_cvt_pk_bf16_f32 v97, v98, v99
	v_cvt_pk_bf16_f32 v98, v100, v101
	v_cvt_pk_bf16_f32 v99, v102, v103
	ds_read2_b64 v[100:103], v183 offset0:8 offset1:10
	v_cndmask_b32_e64 v104, v104, 0, s[16:17]
	s_waitcnt lgkmcnt(0)
	v_mfma_f32_32x32x16_bf16 v[64:79], v[100:103], v[96:99], v[64:79]
	ds_read2_b64 v[100:103], v183 offset0:12 offset1:14
	v_cndmask_b32_e64 v105, v105, 0, s[14:15]
	v_cndmask_b32_e64 v106, v106, 0, s[12:13]
	v_cndmask_b32_e64 v107, v107, 0, s[10:11]
	v_cndmask_b32_e64 v108, v108, 0, s[8:9]
	v_cndmask_b32_e64 v109, v109, 0, s[6:7]
	v_cndmask_b32_e64 v110, v110, 0, s[4:5]
	v_cndmask_b32_e64 v111, v111, 0, s[2:3]
	v_cvt_pk_bf16_f32 v96, v104, v105
	v_cvt_pk_bf16_f32 v97, v106, v107
	v_cvt_pk_bf16_f32 v98, v108, v109
	v_cvt_pk_bf16_f32 v99, v110, v111
	v_add_u32_e32 v108, v171, v169
	s_waitcnt lgkmcnt(0)
	v_mfma_f32_32x32x16_bf16 v[64:79], v[100:103], v[96:99], v[64:79]
	ds_read_b128 v[96:99], v108 offset:53248
	ds_read_b128 v[100:103], v108 offset:53280
	ds_read_b128 v[104:107], v108 offset:53312
	ds_read_b128 v[108:111], v108 offset:53344
	ds_read_b128 v[114:117], v181 offset:34816
	ds_read_b128 v[118:121], v181 offset:34848
	s_waitcnt lgkmcnt(1)
	v_mfma_f32_32x32x16_bf16 v[48:63], v[114:117], v[96:99], v[48:63]
	ds_read_b128 v[114:117], v181 offset:34880
	s_waitcnt lgkmcnt(1)
	v_mfma_f32_32x32x16_bf16 v[48:63], v[118:121], v[100:103], v[48:63]
	s_waitcnt lgkmcnt(0)
	v_mfma_f32_32x32x16_bf16 v[48:63], v[114:117], v[104:107], v[48:63]
	ds_read_b128 v[114:117], v181 offset:34912
	s_waitcnt lgkmcnt(0)
	v_mfma_f32_32x32x16_bf16 v[48:63], v[114:117], v[108:111], v[48:63]
	ds_read_b128 v[114:117], v181 offset:39424
	s_waitcnt lgkmcnt(0)
	v_mfma_f32_32x32x16_bf16 v[32:47], v[114:117], v[96:99], v[32:47]
	ds_read_b128 v[114:117], v181 offset:39456
	s_waitcnt lgkmcnt(0)
	v_mfma_f32_32x32x16_bf16 v[32:47], v[114:117], v[100:103], v[32:47]
	ds_read_b128 v[114:117], v181 offset:39488
	s_waitcnt lgkmcnt(0)
	v_mfma_f32_32x32x16_bf16 v[32:47], v[114:117], v[104:107], v[32:47]
	ds_read_b128 v[114:117], v181 offset:39520
	s_waitcnt lgkmcnt(0)
	v_mfma_f32_32x32x16_bf16 v[32:47], v[114:117], v[108:111], v[32:47]
	ds_read_b128 v[114:117], v181 offset:44032
	s_waitcnt lgkmcnt(0)
	v_mfma_f32_32x32x16_bf16 v[16:31], v[114:117], v[96:99], v[16:31]
	ds_read_b128 v[114:117], v181 offset:44064
	s_waitcnt lgkmcnt(0)
	v_mfma_f32_32x32x16_bf16 v[16:31], v[114:117], v[100:103], v[16:31]
	ds_read_b128 v[114:117], v181 offset:44096
	s_waitcnt lgkmcnt(0)
	v_mfma_f32_32x32x16_bf16 v[16:31], v[114:117], v[104:107], v[16:31]
	ds_read_b128 v[114:117], v181 offset:44128
	s_waitcnt lgkmcnt(0)
	v_mfma_f32_32x32x16_bf16 v[16:31], v[114:117], v[108:111], v[16:31]
	ds_read_b128 v[114:117], v181 offset:48640
	s_waitcnt lgkmcnt(0)
	v_mfma_f32_32x32x16_bf16 v[0:15], v[114:117], v[96:99], v[0:15]
	ds_read_b128 v[96:99], v181 offset:48672
	s_waitcnt lgkmcnt(0)
	v_mfma_f32_32x32x16_bf16 v[0:15], v[96:99], v[100:103], v[0:15]
	ds_read_b128 v[96:99], v181 offset:48704
	s_waitcnt lgkmcnt(0)
	v_mfma_f32_32x32x16_bf16 v[0:15], v[96:99], v[104:107], v[0:15]
	ds_read_b128 v[96:99], v181 offset:48736
	s_waitcnt lgkmcnt(0)
	v_mfma_f32_32x32x16_bf16 v[0:15], v[96:99], v[108:111], v[0:15]
	ds_read_b128 v[96:99], v172
	ds_read_b128 v[100:103], v172 offset:32
	s_waitcnt lgkmcnt(1)
	v_mul_f32_e64 v108, v48, v96
	v_mul_f32_e64 v109, v49, v97
	v_pk_mul_f32 v[114:115], v[50:51], v[98:99]
	ds_read_b128 v[48:51], v172 offset:64
	s_waitcnt lgkmcnt(1)
	v_pk_mul_f32 v[52:53], v[52:53], v[100:101]
	v_pk_mul_f32 v[54:55], v[54:55], v[102:103]
	s_waitcnt lgkmcnt(0)
	v_pk_mul_f32 v[56:57], v[56:57], v[48:49]
	v_pk_mul_f32 v[58:59], v[58:59], v[50:51]
	ds_read_b128 v[48:51], v172 offset:96
	s_waitcnt lgkmcnt(0)
	v_pk_mul_f32 v[60:61], v[60:61], v[48:49]
	v_pk_mul_f32 v[62:63], v[62:63], v[50:51]
	ds_read_b128 v[48:51], v172 offset:128
	s_waitcnt lgkmcnt(0)
	v_pk_mul_f32 v[100:101], v[32:33], v[48:49]
	v_pk_mul_f32 v[96:97], v[34:35], v[50:51]
	ds_read_b128 v[32:35], v172 offset:160
	s_waitcnt lgkmcnt(0)
	v_pk_mul_f32 v[110:111], v[36:37], v[32:33]
	v_pk_mul_f32 v[102:103], v[38:39], v[34:35]
	ds_read_b128 v[32:35], v172 offset:192
	s_waitcnt lgkmcnt(0)
	v_pk_mul_f32 v[104:105], v[40:41], v[32:33]
	v_pk_mul_f32 v[98:99], v[42:43], v[34:35]
	ds_read_b128 v[32:35], v172 offset:224
	s_waitcnt lgkmcnt(0)
	v_pk_mul_f32 v[116:117], v[44:45], v[32:33]
	v_pk_mul_f32 v[106:107], v[46:47], v[34:35]
	ds_read_b128 v[32:35], v172 offset:256
	s_waitcnt lgkmcnt(0)
	v_pk_mul_f32 v[122:123], v[16:17], v[32:33]
	v_pk_mul_f32 v[118:119], v[18:19], v[34:35]
	ds_read_b128 v[16:19], v172 offset:288
	s_waitcnt lgkmcnt(0)
	v_pk_mul_f32 v[130:131], v[20:21], v[16:17]
	v_pk_mul_f32 v[124:125], v[22:23], v[18:19]
	ds_read_b128 v[16:19], v172 offset:320
	s_waitcnt lgkmcnt(0)
	v_pk_mul_f32 v[126:127], v[24:25], v[16:17]
	v_pk_mul_f32 v[120:121], v[26:27], v[18:19]
	ds_read_b128 v[16:19], v172 offset:352
	s_waitcnt lgkmcnt(0)
	v_pk_mul_f32 v[132:133], v[28:29], v[16:17]
	v_pk_mul_f32 v[128:129], v[30:31], v[18:19]
	ds_read_b128 v[16:19], v172 offset:384
	v_lshlrev_b64 v[30:31], 12, v[156:157]
	s_waitcnt lgkmcnt(0)
	v_pk_mul_f32 v[136:137], v[0:1], v[16:17]
	v_pk_mul_f32 v[134:135], v[2:3], v[18:19]
	ds_read_b128 v[0:3], v172 offset:416
	s_waitcnt lgkmcnt(0)
	v_pk_mul_f32 v[144:145], v[4:5], v[0:1]
	v_pk_mul_f32 v[138:139], v[6:7], v[2:3]
	ds_read_b128 v[0:3], v172 offset:448
	s_waitcnt lgkmcnt(0)
	v_pk_mul_f32 v[146:147], v[8:9], v[0:1]
	v_pk_mul_f32 v[140:141], v[10:11], v[2:3]
	ds_read_b128 v[0:3], v172 offset:480
	s_waitcnt lgkmcnt(0)
	s_barrier
	ds_write_b128 v182, v[80:83]
	ds_write_b128 v182, v[84:87] offset:32
	ds_write_b128 v182, v[88:91] offset:64
	ds_write_b128 v182, v[92:95] offset:96
	ds_write_b128 v182, v[64:67] offset:16896
	ds_write_b128 v182, v[68:71] offset:16928
	ds_write_b128 v182, v[72:75] offset:16960
	ds_write_b128 v182, v[76:79] offset:16992
	v_pk_mul_f32 v[148:149], v[12:13], v[0:1]
	v_pk_mul_f32 v[142:143], v[14:15], v[2:3]
	s_waitcnt lgkmcnt(0)
	s_barrier
	ds_read_b128 v[16:19], v173 offset:256
	ds_read_b128 v[12:15], v173 offset:272
	v_lshl_add_u64 v[64:65], v[152:153], 0, v[30:31]
	s_waitcnt lgkmcnt(1)
	v_pk_mul_f32 v[4:5], v[16:17], v[16:17]
	s_waitcnt lgkmcnt(0)
	v_pk_mul_f32 v[6:7], v[12:13], v[12:13]
	v_pk_mul_f32 v[0:1], v[18:19], v[18:19]
	v_pk_mul_f32 v[2:3], v[14:15], v[14:15]
	v_mov_b32_e32 v8, v4
	v_mov_b32_e32 v9, v6
	v_mov_b32_e32 v6, v5
	v_pk_add_f32 v[4:5], v[8:9], v[6:7]
	v_mov_b32_e32 v6, v0
	v_mov_b32_e32 v7, v2
	v_pk_add_f32 v[4:5], v[4:5], v[6:7]
	v_mov_b32_e32 v2, v1
	v_pk_add_f32 v[66:67], v[4:5], v[2:3]
	ds_read_b128 v[4:7], v173 offset:384
	ds_read_b128 v[0:3], v173 offset:400
	s_waitcnt lgkmcnt(1)
	v_pk_mul_f32 v[20:21], v[4:5], v[4:5]
	s_waitcnt lgkmcnt(0)
	v_pk_mul_f32 v[22:23], v[0:1], v[0:1]
	v_pk_mul_f32 v[8:9], v[6:7], v[6:7]
	v_pk_mul_f32 v[10:11], v[2:3], v[2:3]
	v_mov_b32_e32 v24, v20
	v_mov_b32_e32 v25, v22
	v_mov_b32_e32 v22, v21
	v_pk_add_f32 v[20:21], v[24:25], v[22:23]
	v_mov_b32_e32 v22, v8
	v_mov_b32_e32 v23, v10
	v_mov_b32_e32 v10, v9
	v_lshl_add_u64 v[8:9], v[156:157], 0, s[46:47]
	v_lshlrev_b64 v[8:9], 8, v[8:9]
	v_pk_add_f32 v[20:21], v[20:21], v[22:23]
	v_lshl_add_u64 v[28:29], v[150:151], 0, v[8:9]
	v_pk_add_f32 v[68:69], v[20:21], v[10:11]
	ds_read_b128 v[48:51], v173
	ds_read_b128 v[40:43], v173 offset:16
	ds_read_b128 v[32:35], v173 offset:128
	ds_read_b128 v[28:31], v173 offset:144
	global_load_dwordx4 v[36:39], v[154:155], off offset:16
	global_load_dwordx4 v[44:47], v[154:155], off
	s_waitcnt lgkmcnt(3)
	v_mov_b32_e32 v84, v49
	s_waitcnt lgkmcnt(2)
	v_mov_b32_e32 v85, v41
	v_mov_b32_e32 v78, v48
	v_mov_b32_e32 v79, v40
	v_pk_mul_f32 v[84:85], v[84:85], v[84:85]
	s_waitcnt lgkmcnt(1)
	v_mov_b32_e32 v90, v33
	v_pk_fma_f32 v[78:79], v[78:79], v[78:79], v[84:85]
	s_waitcnt lgkmcnt(0)
	v_mov_b32_e32 v91, v29
	v_mov_b32_e32 v74, v51
	v_mov_b32_e32 v75, v43
	v_mov_b32_e32 v88, v32
	v_mov_b32_e32 v89, v28
	v_pk_mul_f32 v[90:91], v[90:91], v[90:91]
	v_mov_b32_e32 v86, v35
	v_pk_fma_f32 v[88:89], v[88:89], v[88:89], v[90:91]
	v_mov_b32_e32 v87, v31
	v_add_u32_e32 v156, 64, v156
	s_waitcnt vmcnt(2)
	v_lshlrev_b32_e32 v80, 16, v229
	v_and_b32_e32 v81, 0xffff0000, v229
	v_lshlrev_b32_e32 v82, 16, v228
	v_and_b32_e32 v83, 0xffff0000, v228
	v_mov_b32_e32 v70, v50
	v_mov_b32_e32 v71, v42
	v_pk_fma_f32 v[70:71], v[70:71], v[70:71], v[78:79]
	v_lshlrev_b32_e32 v76, 16, v230
	v_and_b32_e32 v77, 0xffff0000, v230
	v_pk_fma_f32 v[84:85], v[74:75], v[74:75], v[70:71]
	v_lshlrev_b32_e32 v78, 16, v231
	v_and_b32_e32 v79, 0xffff0000, v231
	v_lshlrev_b32_e32 v72, 16, v225
	v_and_b32_e32 v73, 0xffff0000, v225
	v_lshlrev_b32_e32 v74, 16, v224
	v_and_b32_e32 v75, 0xffff0000, v224
	v_mov_b32_e32 v24, v34
	v_mov_b32_e32 v25, v30
	v_pk_fma_f32 v[24:25], v[24:25], v[24:25], v[88:89]
	v_lshlrev_b32_e32 v70, 16, v226
	v_and_b32_e32 v71, 0xffff0000, v226
	v_pk_fma_f32 v[24:25], v[86:87], v[86:87], v[24:25]
	v_add_f32_e32 v26, v84, v85
	v_add_f32_e32 v24, v26, v24
	v_add_f32_e32 v24, v24, v25
	v_add_f32_e32 v24, v24, v66
	v_add_f32_e32 v24, v24, v67
	v_add_f32_e32 v24, v24, v68
	v_add_f32_e32 v24, v24, v69
	s_nop 1
	v_add_f32_dpp v24, v24, v24 quad_perm:[1,0,3,2] row_mask:0xf bank_mask:0xf
	v_lshlrev_b32_e32 v26, 16, v227
	v_and_b32_e32 v27, 0xffff0000, v227
	v_add_f32_dpp v24, v24, v24 quad_perm:[2,3,0,1] row_mask:0xf bank_mask:0xf
	v_fmamk_f32 v24, v24, 0x3c000000, v161
	v_cmp_gt_f32_e64 s[36:37], s70, v24
	v_mul_f32_e32 v25, 0x4b800000, v24
	s_nop 0
	v_cndmask_b32_e64 v24, v24, v25, s[36:37]
	v_rsq_f32_e32 v24, v24
	s_nop 0
	v_mul_f32_e32 v25, 0x45800000, v24
	v_cndmask_b32_e64 v24, v24, v25, s[36:37]
	v_pk_mul_f32 v[48:49], v[48:49], v[24:25] op_sel_hi:[1,0]
	v_pk_mul_f32 v[40:41], v[40:41], v[24:25] op_sel_hi:[1,0]
	s_waitcnt vmcnt(0)
	v_pk_mul_f32 v[44:45], v[44:45], v[48:49]
	v_pk_mul_f32 v[48:49], v[50:51], v[24:25] op_sel_hi:[1,0]
	v_pk_mul_f32 v[36:37], v[36:37], v[40:41]
	v_pk_mul_f32 v[46:47], v[46:47], v[48:49]
	v_pk_mul_f32 v[44:45], v[44:45], v[82:83]
	v_pk_mul_f32 v[46:47], v[46:47], v[80:81]
	v_pk_mul_f32 v[36:37], v[36:37], v[76:77]
	v_cvt_pk_bf16_f32 v44, v44, v45
	v_cvt_pk_bf16_f32 v45, v46, v47
	v_cvt_pk_bf16_f32 v46, v36, v37
	v_pk_mul_f32 v[36:37], v[42:43], v[24:25] op_sel_hi:[1,0]
	v_pk_mul_f32 v[32:33], v[32:33], v[24:25] op_sel_hi:[1,0]
	v_pk_mul_f32 v[36:37], v[36:37], v[38:39]
	v_pk_mul_f32 v[34:35], v[34:35], v[24:25] op_sel_hi:[1,0]
	v_pk_mul_f32 v[36:37], v[36:37], v[78:79]
	v_pk_mul_f32 v[28:29], v[28:29], v[24:25] op_sel_hi:[1,0]
	v_cvt_pk_bf16_f32 v47, v36, v37
	global_store_dwordx4 v[64:65], v[44:47], off
	global_load_dwordx4 v[36:39], v[154:155], off offset:144
	global_load_dwordx4 v[40:43], v[154:155], off offset:128
	v_pk_mul_f32 v[16:17], v[16:17], v[24:25] op_sel_hi:[1,0]
	v_pk_mul_f32 v[18:19], v[18:19], v[24:25] op_sel_hi:[1,0]
	v_pk_mul_f32 v[12:13], v[12:13], v[24:25] op_sel_hi:[1,0]
	v_pk_mul_f32 v[4:5], v[4:5], v[24:25] op_sel_hi:[1,0]
	v_pk_mul_f32 v[6:7], v[6:7], v[24:25] op_sel_hi:[1,0]
	v_pk_mul_f32 v[0:1], v[0:1], v[24:25] op_sel_hi:[1,0]
	s_waitcnt vmcnt(1)
	v_pk_mul_f32 v[28:29], v[28:29], v[36:37]
	s_waitcnt vmcnt(0)
	v_pk_mul_f32 v[32:33], v[32:33], v[40:41]
	v_pk_mul_f32 v[34:35], v[34:35], v[42:43]
	v_pk_mul_f32 v[32:33], v[32:33], v[74:75]
	v_pk_mul_f32 v[34:35], v[34:35], v[72:73]
	v_pk_mul_f32 v[28:29], v[28:29], v[70:71]
	v_cvt_pk_bf16_f32 v32, v32, v33
	v_cvt_pk_bf16_f32 v33, v34, v35
	v_cvt_pk_bf16_f32 v34, v28, v29
	v_pk_mul_f32 v[28:29], v[30:31], v[24:25] op_sel_hi:[1,0]
	s_nop 0
	v_pk_mul_f32 v[28:29], v[28:29], v[38:39]
	s_nop 0
	v_pk_mul_f32 v[26:27], v[28:29], v[26:27]
	s_nop 0
	v_cvt_pk_bf16_f32 v35, v26, v27
	global_store_dwordx4 v[64:65], v[32:35], off offset:64
	global_load_dwordx4 v[26:29], v[154:155], off offset:272
	s_nop 0
	global_load_dwordx4 v[30:33], v[154:155], off offset:256
	s_waitcnt vmcnt(1)
	v_pk_mul_f32 v[12:13], v[12:13], v[26:27]
	s_waitcnt vmcnt(0)
	v_pk_mul_f32 v[16:17], v[16:17], v[30:31]
	v_lshlrev_b32_e32 v30, 16, v220
	v_and_b32_e32 v31, 0xffff0000, v220
	v_pk_mul_f32 v[18:19], v[18:19], v[32:33]
	v_lshlrev_b32_e32 v20, 16, v221
	v_and_b32_e32 v21, 0xffff0000, v221
	v_pk_mul_f32 v[16:17], v[16:17], v[30:31]
	v_pk_mul_f32 v[18:19], v[18:19], v[20:21]
	v_cvt_pk_bf16_f32 v16, v16, v17
	v_cvt_pk_bf16_f32 v17, v18, v19
	v_lshlrev_b32_e32 v18, 16, v222
	v_and_b32_e32 v19, 0xffff0000, v222
	v_pk_mul_f32 v[12:13], v[12:13], v[18:19]
	s_nop 0
	v_cvt_pk_bf16_f32 v18, v12, v13
	v_pk_mul_f32 v[12:13], v[14:15], v[24:25] op_sel_hi:[1,0]
	v_lshlrev_b32_e32 v14, 16, v223
	v_pk_mul_f32 v[12:13], v[12:13], v[28:29]
	v_and_b32_e32 v15, 0xffff0000, v223
	v_pk_mul_f32 v[12:13], v[12:13], v[14:15]
	s_nop 0
	v_cvt_pk_bf16_f32 v19, v12, v13
	global_store_dwordx4 v[64:65], v[16:19], off offset:128
	global_load_dwordx4 v[12:15], v[154:155], off offset:400
	s_nop 0
	global_load_dwordx4 v[16:19], v[154:155], off offset:384
	s_waitcnt vmcnt(1)
	v_pk_mul_f32 v[0:1], v[0:1], v[12:13]
	s_waitcnt vmcnt(0)
	v_pk_mul_f32 v[4:5], v[4:5], v[16:17]
	v_lshlrev_b32_e32 v16, 16, v216
	v_and_b32_e32 v17, 0xffff0000, v216
	v_pk_mul_f32 v[6:7], v[6:7], v[18:19]
	v_lshlrev_b32_e32 v8, 16, v217
	v_and_b32_e32 v9, 0xffff0000, v217
	v_pk_mul_f32 v[4:5], v[4:5], v[16:17]
	v_pk_mul_f32 v[6:7], v[6:7], v[8:9]
	v_cvt_pk_bf16_f32 v4, v4, v5
	v_cvt_pk_bf16_f32 v5, v6, v7
	v_lshlrev_b32_e32 v6, 16, v218
	v_and_b32_e32 v7, 0xffff0000, v218
	v_pk_mul_f32 v[0:1], v[0:1], v[6:7]
	s_nop 0
	v_cvt_pk_bf16_f32 v6, v0, v1
	v_pk_mul_f32 v[0:1], v[2:3], v[24:25] op_sel_hi:[1,0]
	v_lshlrev_b32_e32 v2, 16, v219
	v_pk_mul_f32 v[0:1], v[0:1], v[14:15]
	v_and_b32_e32 v3, 0xffff0000, v219
	v_pk_mul_f32 v[0:1], v[0:1], v[2:3]
	s_nop 0
	v_cvt_pk_bf16_f32 v7, v0, v1
	global_store_dwordx4 v[64:65], v[4:7], off offset:192
	s_cbranch_scc1 .LBB0_425
